# all remaining inner loop headers (rmsnorm, compressed branch, prologue, spin loops) also aligned to 64 bytes
# baseline (speedup 1.0000x reference)
; __global__ void __launch_bounds__(256, 2) fwd_megakernel(Params p) {
;     ...
;     cg::grid_group grid = cg::this_grid();
;     if (p.ws == nullptr) grid.sync();
.LBB0_10:
	s_or_b64 exec, exec, s[6:7]
	v_mov_b32_e32 v2, 0
	global_load_dword v3, v2, s[4:5] offset:32 sc1
	v_and_b32_e32 v1, 0xffff0000, v1
	s_waitcnt vmcnt(0)
	v_and_b32_e32 v3, 0xffff0000, v3
	v_cmp_eq_u32_e32 vcc, v3, v1
	s_and_b64 exec, exec, vcc
	s_cbranch_execz .LBB0_13
	s_mov_b64 s[6:7], 0
	.p2alignl 6, 3212836864

; __device__ __forceinline__ void rmsnorm_phase(const float* x, const float* g, bf16_t* outb, float* outf) {
;     const int lane = threadIdx.x & 63;
;     const int gw = blockIdx.x * 4 + (threadIdx.x >> 6), nw = gridDim.x * 4;
;     f32x4 gv[4];
; #pragma unroll
;     for (int i = 0; i < 4; ++i) gv[i] = *(const f32x4*)(g + (lane + i * 64) * 4);
;     for (int row = gw; row < T; row += nw) {
;         const float* xr = x + (size_t)row * D;
;         f32x4 v[4];
;         float ss = 0.f;
; #pragma unroll
;         for (int i = 0; i < 4; ++i) { v[i] = __builtin_nontemporal_load((const f32x4*)(xr + (lane + i * 64) * 4)); ss += v[i][0] * v[i][0] + v[i][1] * v[i][1] + v[i][2] * v[i][2] + v[i][3] * v[i][3]; }
; #pragma unroll
;         for (int o = 32; o >= 1; o >>= 1) ss += __shfl_xor(ss, o);
.LBB0_98:
	v_lshrrev_b32_e32 v116, 6, v114
	v_readlane_b32 s0, v245, 0
	v_and_b32_e32 v136, 0xfc, v0
	s_lshl_b32 s10, s58, 2
	v_lshl_add_u32 v112, s0, 2, v116
	s_mov_b32 s0, 0x8000
	v_ashrrev_i32_e32 v113, 31, v112
	v_lshlrev_b32_e32 v146, 2, v136
	v_mbcnt_lo_u32_b32 v138, -1, 0
	v_and_b32_e32 v115, 63, v114
	v_cmp_gt_i32_e64 s[2:3], s0, v112
	s_mov_b64 s[0:1], exec
	s_nop 0
	v_writelane_b32 v245, s2, 49
	s_nop 1
	v_writelane_b32 v245, s3, 50
	s_and_b64 s[2:3], s[0:1], s[2:3]
	s_mov_b64 exec, s[2:3]
	s_cbranch_execz .LBB0_101
	v_readlane_b32 s12, v245, 10
	v_readlane_b32 s13, v245, 11
	v_readlane_b32 s14, v245, 12
	v_readlane_b32 s15, v245, 13
	v_readlane_b32 s16, v245, 14
	v_readlane_b32 s17, v245, 15
	s_mov_b64 s[4:5], s[12:13]
	s_mov_b64 s[6:7], s[14:15]
	global_load_dwordx4 v[0:3], v146, s[6:7]
	global_load_dwordx4 v[4:7], v146, s[6:7] offset:1024
	global_load_dwordx4 v[8:11], v146, s[6:7] offset:2048
	global_load_dwordx4 v[12:15], v146, s[6:7] offset:3072
	v_mbcnt_hi_u32_b32 v16, -1, v138
	v_and_b32_e32 v17, 64, v16
	v_add_u32_e32 v17, 64, v17
	v_xor_b32_e32 v18, 32, v16
	v_cmp_lt_i32_e32 vcc, v18, v17
	s_mov_b64 s[8:9], s[16:17]
	s_mov_b64 s[2:3], 0x3800000
	v_cndmask_b32_e32 v18, v16, v18, vcc
	v_lshlrev_b32_e32 v20, 2, v18
	v_xor_b32_e32 v18, 16, v16
	v_cmp_lt_i32_e32 vcc, v18, v17
	s_ashr_i32 s11, s10, 31
	s_mov_b64 s[6:7], 0
	v_cndmask_b32_e32 v18, v16, v18, vcc
	v_lshlrev_b32_e32 v21, 2, v18
	v_xor_b32_e32 v18, 8, v16
	v_cmp_lt_i32_e32 vcc, v18, v17
	v_mov_b32_e32 v26, 0x358637bd
	s_mov_b32 s8, 0x800000
	v_cndmask_b32_e32 v18, v16, v18, vcc
	v_lshlrev_b32_e32 v22, 2, v18
	v_xor_b32_e32 v18, 4, v16
	v_cmp_lt_i32_e32 vcc, v18, v17
	s_movk_i32 s9, 0x7fff
	v_mov_b32_e32 v27, v112
	v_cndmask_b32_e32 v18, v16, v18, vcc
	v_lshlrev_b32_e32 v23, 2, v18
	v_xor_b32_e32 v18, 2, v16
	v_cmp_lt_i32_e32 vcc, v18, v17
	v_readlane_b32 s18, v245, 16
	v_readlane_b32 s19, v245, 17
	v_cndmask_b32_e32 v18, v16, v18, vcc
	v_lshlrev_b32_e32 v24, 2, v18
	v_xor_b32_e32 v18, 1, v16
	v_cmp_lt_i32_e32 vcc, v18, v17
	v_readlane_b32 s20, v245, 18
	v_readlane_b32 s21, v245, 19
	v_cndmask_b32_e32 v16, v16, v18, vcc
	v_lshlrev_b32_e32 v25, 2, v16
	v_lshlrev_b64 v[16:17], 11, v[112:113]
	v_lshlrev_b64 v[18:19], 12, v[112:113]
	v_lshl_or_b32 v16, v115, 3, v16
	v_lshl_or_b32 v18, v115, 4, v18
	v_lshl_add_u64 v[16:17], s[56:57], 0, v[16:17]
	v_lshl_add_u64 v[18:19], s[4:5], 0, v[18:19]
	s_mov_b64 s[4:5], 0xc00
	v_lshl_add_u64 v[16:17], v[16:17], 0, s[2:3]
	s_lshl_b64 s[2:3], s[10:11], 11
	v_lshl_add_u64 v[18:19], v[18:19], 0, s[4:5]
	s_lshl_b64 s[4:5], s[10:11], 12
	v_readlane_b32 s22, v245, 20
	v_readlane_b32 s23, v245, 21
	v_readlane_b32 s24, v245, 22
	v_readlane_b32 s25, v245, 23
	v_readlane_b32 s26, v245, 24
	v_readlane_b32 s27, v245, 25
	.p2alignl 6, 3212836864

; __device__ __forceinline__ unsigned xb_ld(unsigned* p)              { return __hip_atomic_load(p, __ATOMIC_RELAXED, __HIP_MEMORY_SCOPE_AGENT); }
; __device__ __forceinline__ void xcd_barrier_complete(unsigned* bar, unsigned x, unsigned& nloc, unsigned& nx) {
;     const unsigned G = gridDim.x * gridDim.y * gridDim.z;
;     unsigned sum, cnt, mine, sp = 0u;
;     for (;;) {
;         sum = 0u; cnt = 0u; mine = 0u;
; #pragma unroll
;         for (unsigned j = 0; j < 16; ++j) { const unsigned c = xb_ld(&bar[XB_XCNT(j)]); sum += c; cnt += (c > 0u) ? 1u : 0u; mine = (j == x) ? c : mine; }
;         if (sum == G) break;
;         __builtin_amdgcn_s_sleep(1);
;         if ((++sp & 255u) == 0u) { if (xb_ld(&bar[XB_TMO])) break; if (sp > XB_SPIN_CAP) { atomicAdd(&bar[XB_TMO], 1u); break; } }
;     }
;     nloc = mine > 0u ? mine : 1u; nx = cnt > 0u ? cnt : 1u;
.LBB0_105:
	s_or_b64 exec, exec, s[10:11]
	s_and_b64 s[10:11], exec, s[6:7]
	s_or_b64 s[0:1], s[10:11], s[0:1]
	s_andn2_b64 s[4:5], s[4:5], exec
	s_and_b64 s[10:11], s[8:9], exec
	s_or_b64 s[4:5], s[4:5], s[10:11]
	s_andn2_b64 exec, exec, s[0:1]
	s_cbranch_execz .LBB0_113
	.p2alignl 6, 3212836864

; __device__ __forceinline__ unsigned xb_ld(unsigned* p)              { return __hip_atomic_load(p, __ATOMIC_RELAXED, __HIP_MEMORY_SCOPE_AGENT); }
; #define XB_SPIN(cond, bar) do { unsigned _sp = 0; while (cond) { __builtin_amdgcn_s_sleep(1); \
;     if ((++_sp & 255u) == 0u) { if (xb_ld(&(bar)[XB_TMO])) break; if (_sp > XB_SPIN_CAP) { atomicAdd(&(bar)[XB_TMO], 1u); break; } } } } while (0)
; __device__ __forceinline__ void gsync(const XcdBarrier& b) {
;     ...
;             else XB_SPIN(xb_ld(&bar[XB_TOPGEN]) == tg, bar);
.LBB0_119:
	s_or_b64 exec, exec, s[18:19]
	s_and_b64 s[14:15], exec, s[14:15]
	s_or_b64 s[8:9], s[14:15], s[8:9]
	s_andn2_b64 s[10:11], s[10:11], exec
	s_and_b64 s[14:15], s[12:13], exec
	s_or_b64 s[10:11], s[10:11], s[14:15]
	s_andn2_b64 exec, exec, s[8:9]
	s_cbranch_execz .LBB0_126
	.p2alignl 6, 3212836864

; __device__ __forceinline__ unsigned xb_ld(unsigned* p)              { return __hip_atomic_load(p, __ATOMIC_RELAXED, __HIP_MEMORY_SCOPE_AGENT); }
; #define XB_SPIN(cond, bar) do { unsigned _sp = 0; while (cond) { __builtin_amdgcn_s_sleep(1); \
;     if ((++_sp & 255u) == 0u) { if (xb_ld(&(bar)[XB_TMO])) break; if (_sp > XB_SPIN_CAP) { atomicAdd(&(bar)[XB_TMO], 1u); break; } } } } while (0)
; __device__ __forceinline__ void gsync(const XcdBarrier& b) {
;     ...
;             XB_SPIN(xb_ld(&bar[XB_XGEN(bx)]) == gen, bar);
.LBB0_133:
	s_or_b64 exec, exec, s[20:21]
	s_xor_b64 s[14:15], s[14:15], -1
	s_and_b64 s[16:17], exec, s[18:19]
	s_or_b64 s[10:11], s[16:17], s[10:11]
	s_andn2_b64 s[12:13], s[12:13], exec
	s_and_b64 s[14:15], s[14:15], exec
	s_or_b64 s[12:13], s[12:13], s[14:15]
	s_andn2_b64 exec, exec, s[10:11]
	s_cbranch_execz .LBB0_140
	.p2alignl 6, 3212836864

; __device__ __forceinline__ void rmsnorm_phase(const float* x, const float* g, bf16_t* outb, float* outf) {
;     const int lane = threadIdx.x & 63;
;     const int gw = blockIdx.x * 4 + (threadIdx.x >> 6), nw = gridDim.x * 4;
;     f32x4 gv[4];
; #pragma unroll
;     for (int i = 0; i < 4; ++i) gv[i] = *(const f32x4*)(g + (lane + i * 64) * 4);
;     for (int row = gw; row < T; row += nw) {
;         const float* xr = x + (size_t)row * D;
;         f32x4 v[4];
;         float ss = 0.f;
; #pragma unroll
;         for (int i = 0; i < 4; ++i) { v[i] = __builtin_nontemporal_load((const f32x4*)(xr + (lane + i * 64) * 4)); ss += v[i][0] * v[i][0] + v[i][1] * v[i][1] + v[i][2] * v[i][2] + v[i][3] * v[i][3]; }
; #pragma unroll
;         for (int o = 32; o >= 1; o >>= 1) ss += __shfl_xor(ss, o);
.LBB0_508:
	s_or_b64 exec, exec, s[34:35]
	s_waitcnt lgkmcnt(0)
	s_barrier
	s_mov_b64 s[0:1], exec
	v_readlane_b32 s4, v245, 49
	v_readlane_b32 s5, v245, 50
	s_and_b64 s[4:5], s[0:1], s[4:5]
	v_readlane_b32 s40, v245, 51
	v_readlane_b32 s41, v245, 52
	s_mov_b64 exec, s[4:5]
	s_cbranch_execz .LBB0_511
	v_readlane_b32 s4, v245, 10
	v_readlane_b32 s8, v245, 14
	v_readlane_b32 s9, v245, 15
	s_nop 4
	global_load_dwordx4 v[0:3], v146, s[8:9]
	global_load_dwordx4 v[4:7], v146, s[8:9] offset:1024
	global_load_dwordx4 v[8:11], v146, s[8:9] offset:2048
	global_load_dwordx4 v[12:15], v146, s[8:9] offset:3072
	v_cmp_lt_i32_e32 vcc, v140, v138
	v_lshlrev_b64 v[18:19], 12, v[112:113]
	v_readlane_b32 s5, v245, 11
	v_cndmask_b32_e32 v16, v117, v140, vcc
	v_cmp_lt_i32_e32 vcc, v139, v138
	v_lshlrev_b32_e32 v20, 2, v16
	v_readlane_b32 s6, v245, 12
	v_cndmask_b32_e32 v16, v117, v139, vcc
	v_lshlrev_b32_e32 v21, 2, v16
	v_xor_b32_e32 v16, 8, v117
	v_cmp_lt_i32_e32 vcc, v16, v138
	v_readlane_b32 s7, v245, 13
	v_lshl_or_b32 v18, v115, 4, v18
	v_cndmask_b32_e32 v16, v117, v16, vcc
	v_lshlrev_b32_e32 v22, 2, v16
	v_xor_b32_e32 v16, 4, v117
	v_cmp_lt_i32_e32 vcc, v16, v138
	v_readlane_b32 s10, v245, 16
	v_readlane_b32 s11, v245, 17
	v_cndmask_b32_e32 v16, v117, v16, vcc
	v_lshlrev_b32_e32 v23, 2, v16
	v_xor_b32_e32 v16, 2, v117
	v_cmp_lt_i32_e32 vcc, v16, v138
	s_mov_b64 s[4:5], 0x3800000
	s_ashr_i32 s41, s40, 31
	v_cndmask_b32_e32 v16, v117, v16, vcc
	v_lshlrev_b32_e32 v24, 2, v16
	v_xor_b32_e32 v16, 1, v117
	v_cmp_lt_i32_e32 vcc, v16, v138
	v_lshl_add_u64 v[18:19], s[54:55], 0, v[18:19]
	s_mov_b64 s[6:7], 0xc00
	v_cndmask_b32_e32 v16, v117, v16, vcc
	v_lshlrev_b32_e32 v25, 2, v16
	v_lshlrev_b64 v[16:17], 11, v[112:113]
	v_lshl_or_b32 v16, v115, 3, v16
	v_lshl_add_u64 v[16:17], s[56:57], 0, v[16:17]
	v_lshl_add_u64 v[16:17], v[16:17], 0, s[4:5]
	s_lshl_b64 s[4:5], s[40:41], 11
	v_lshl_add_u64 v[18:19], v[18:19], 0, s[6:7]
	s_lshl_b64 s[6:7], s[40:41], 12
	s_mov_b64 s[8:9], 0
	v_mov_b32_e32 v26, 0x358637bd
	s_mov_b32 s10, 0x800000
	s_movk_i32 s11, 0x7fff
	v_mov_b32_e32 v27, v112
	v_readlane_b32 s12, v245, 18
	v_readlane_b32 s13, v245, 19
	v_readlane_b32 s14, v245, 20
	v_readlane_b32 s15, v245, 21
	v_readlane_b32 s16, v245, 22
	v_readlane_b32 s17, v245, 23
	v_readlane_b32 s18, v245, 24
	v_readlane_b32 s19, v245, 25
	.p2alignl 6, 3212836864

; __device__ __forceinline__ unsigned xb_ld(unsigned* p)              { return __hip_atomic_load(p, __ATOMIC_RELAXED, __HIP_MEMORY_SCOPE_AGENT); }
; __device__ __forceinline__ void xcd_barrier_complete(unsigned* bar, unsigned x, unsigned& nloc, unsigned& nx) {
;     const unsigned G = gridDim.x * gridDim.y * gridDim.z;
;     unsigned sum, cnt, mine, sp = 0u;
;     for (;;) {
;         sum = 0u; cnt = 0u; mine = 0u;
; #pragma unroll
;         for (unsigned j = 0; j < 16; ++j) { const unsigned c = xb_ld(&bar[XB_XCNT(j)]); sum += c; cnt += (c > 0u) ? 1u : 0u; mine = (j == x) ? c : mine; }
;         if (sum == G) break;
;         __builtin_amdgcn_s_sleep(1);
;         if ((++sp & 255u) == 0u) { if (xb_ld(&bar[XB_TMO])) break; if (sp > XB_SPIN_CAP) { atomicAdd(&bar[XB_TMO], 1u); break; } }
;     }
;     nloc = mine > 0u ? mine : 1u; nx = cnt > 0u ? cnt : 1u;
.LBB0_627:
	s_or_b64 exec, exec, s[12:13]
	s_and_b64 s[12:13], exec, s[8:9]
	s_or_b64 s[0:1], s[12:13], s[0:1]
	s_andn2_b64 s[6:7], s[6:7], exec
	s_and_b64 s[12:13], s[10:11], exec
	s_or_b64 s[6:7], s[6:7], s[12:13]
	s_andn2_b64 exec, exec, s[0:1]
	s_cbranch_execz .LBB0_635
	.p2alignl 6, 3212836864

; __device__ __forceinline__ unsigned xb_ld(unsigned* p)              { return __hip_atomic_load(p, __ATOMIC_RELAXED, __HIP_MEMORY_SCOPE_AGENT); }
; #define XB_SPIN(cond, bar) do { unsigned _sp = 0; while (cond) { __builtin_amdgcn_s_sleep(1); \
;     if ((++_sp & 255u) == 0u) { if (xb_ld(&(bar)[XB_TMO])) break; if (_sp > XB_SPIN_CAP) { atomicAdd(&(bar)[XB_TMO], 1u); break; } } } } while (0)
; __device__ __forceinline__ void gsync(const XcdBarrier& b) {
;     ...
;             else XB_SPIN(xb_ld(&bar[XB_TOPGEN]) == tg, bar);
.LBB0_641:
	s_or_b64 exec, exec, s[20:21]
	s_and_b64 s[16:17], exec, s[16:17]
	s_or_b64 s[10:11], s[16:17], s[10:11]
	s_andn2_b64 s[12:13], s[12:13], exec
	s_and_b64 s[16:17], s[14:15], exec
	s_or_b64 s[12:13], s[12:13], s[16:17]
	s_andn2_b64 exec, exec, s[10:11]
	s_cbranch_execz .LBB0_648
	.p2alignl 6, 3212836864

; __device__ __forceinline__ unsigned xb_ld(unsigned* p)              { return __hip_atomic_load(p, __ATOMIC_RELAXED, __HIP_MEMORY_SCOPE_AGENT); }
; #define XB_SPIN(cond, bar) do { unsigned _sp = 0; while (cond) { __builtin_amdgcn_s_sleep(1); \
;     if ((++_sp & 255u) == 0u) { if (xb_ld(&(bar)[XB_TMO])) break; if (_sp > XB_SPIN_CAP) { atomicAdd(&(bar)[XB_TMO], 1u); break; } } } } while (0)
; __device__ __forceinline__ void gsync(const XcdBarrier& b) {
;     ...
;             XB_SPIN(xb_ld(&bar[XB_XGEN(bx)]) == gen, bar);
.LBB0_655:
	s_or_b64 exec, exec, s[22:23]
	s_xor_b64 s[16:17], s[16:17], -1
	s_and_b64 s[18:19], exec, s[20:21]
	s_or_b64 s[12:13], s[18:19], s[12:13]
	s_andn2_b64 s[14:15], s[14:15], exec
	s_and_b64 s[16:17], s[16:17], exec
	s_or_b64 s[14:15], s[14:15], s[16:17]
	s_andn2_b64 exec, exec, s[12:13]
	s_cbranch_execz .LBB0_662
	.p2alignl 6, 3212836864

; __device__ __forceinline__ void rmsnorm_phase(const float* x, const float* g, bf16_t* outb, float* outf) {
;     const int lane = threadIdx.x & 63;
;     const int gw = blockIdx.x * 4 + (threadIdx.x >> 6), nw = gridDim.x * 4;
;     f32x4 gv[4];
; #pragma unroll
;     for (int i = 0; i < 4; ++i) gv[i] = *(const f32x4*)(g + (lane + i * 64) * 4);
;     for (int row = gw; row < T; row += nw) {
;         const float* xr = x + (size_t)row * D;
;         f32x4 v[4];
;         float ss = 0.f;
; #pragma unroll
;         for (int i = 0; i < 4; ++i) { v[i] = __builtin_nontemporal_load((const f32x4*)(xr + (lane + i * 64) * 4)); ss += v[i][0] * v[i][0] + v[i][1] * v[i][1] + v[i][2] * v[i][2] + v[i][3] * v[i][3]; }
; #pragma unroll
;         for (int o = 32; o >= 1; o >>= 1) ss += __shfl_xor(ss, o);
.LBB0_667:
	s_or_b64 exec, exec, s[2:3]
	v_or_b32_e32 v0, 0x100, v136
	v_or_b32_e32 v1, 0x200, v136
	v_or_b32_e32 v2, 0x300, v136
	v_lshlrev_b32_e32 v168, 2, v0
	v_lshlrev_b32_e32 v167, 2, v1
	v_lshlrev_b32_e32 v169, 2, v2
	s_waitcnt lgkmcnt(0)
	s_barrier
	s_mov_b64 s[0:1], exec
	v_readlane_b32 s2, v245, 49
	v_readlane_b32 s3, v245, 50
	s_and_b64 s[2:3], s[0:1], s[2:3]
	s_mov_b64 exec, s[2:3]
	s_cbranch_execz .LBB0_670
	v_readlane_b32 s8, v245, 10
	v_readlane_b32 s10, v245, 12
	v_readlane_b32 s11, v245, 13
	s_mov_b64 s[6:7], s[10:11]
	s_add_u32 s2, s6, 0x1000
	s_addc_u32 s3, s7, 0
	global_load_dwordx4 v[0:3], v168, s[2:3]
	global_load_dwordx4 v[4:7], v167, s[2:3]
	global_load_dwordx4 v[8:11], v146, s[2:3]
	global_load_dwordx4 v[12:15], v169, s[2:3]
	v_cmp_lt_i32_e32 vcc, v140, v138
	v_lshlrev_b64 v[18:19], 12, v[112:113]
	v_lshl_or_b32 v18, v115, 4, v18
	v_cndmask_b32_e32 v16, v117, v140, vcc
	v_cmp_lt_i32_e32 vcc, v139, v138
	v_lshlrev_b32_e32 v20, 2, v16
	v_readlane_b32 s9, v245, 11
	v_cndmask_b32_e32 v16, v117, v139, vcc
	v_lshlrev_b32_e32 v21, 2, v16
	v_xor_b32_e32 v16, 8, v117
	v_cmp_lt_i32_e32 vcc, v16, v138
	s_mov_b64 s[2:3], 0x3800000
	s_ashr_i32 s41, s40, 31
	v_cndmask_b32_e32 v16, v117, v16, vcc
	v_lshlrev_b32_e32 v22, 2, v16
	v_xor_b32_e32 v16, 4, v117
	v_cmp_lt_i32_e32 vcc, v16, v138
	v_lshl_add_u64 v[18:19], s[54:55], 0, v[18:19]
	s_mov_b64 s[6:7], 0xc00
	v_cndmask_b32_e32 v16, v117, v16, vcc
	v_lshlrev_b32_e32 v23, 2, v16
	v_xor_b32_e32 v16, 2, v117
	v_cmp_lt_i32_e32 vcc, v16, v138
	v_lshl_add_u64 v[18:19], v[18:19], 0, s[6:7]
	s_lshl_b64 s[6:7], s[40:41], 12
	v_cndmask_b32_e32 v16, v117, v16, vcc
	v_lshlrev_b32_e32 v24, 2, v16
	v_xor_b32_e32 v16, 1, v117
	v_cmp_lt_i32_e32 vcc, v16, v138
	s_mov_b64 s[8:9], 0
	v_mov_b32_e32 v26, 0x358637bd
	v_cndmask_b32_e32 v16, v117, v16, vcc
	v_lshlrev_b32_e32 v25, 2, v16
	v_lshlrev_b64 v[16:17], 11, v[112:113]
	v_lshl_or_b32 v16, v115, 3, v16
	v_lshl_add_u64 v[16:17], s[56:57], 0, v[16:17]
	v_lshl_add_u64 v[16:17], v[16:17], 0, s[2:3]
	s_lshl_b64 s[2:3], s[40:41], 11
	s_mov_b32 s10, 0x800000
	s_movk_i32 s11, 0x7fff
	v_mov_b32_e32 v27, v112
	v_readlane_b32 s12, v245, 14
	v_readlane_b32 s13, v245, 15
	v_readlane_b32 s14, v245, 16
	v_readlane_b32 s15, v245, 17
	v_readlane_b32 s16, v245, 18
	v_readlane_b32 s17, v245, 19
	v_readlane_b32 s18, v245, 20
	v_readlane_b32 s19, v245, 21
	v_readlane_b32 s20, v245, 22
	v_readlane_b32 s21, v245, 23
	v_readlane_b32 s22, v245, 24
	v_readlane_b32 s23, v245, 25
	.p2alignl 6, 3212836864

; __global__ void __launch_bounds__(256, 2) fwd_megakernel(Params p) {
;     ...
;         for (int r = 0; r * G < 4096; ++r) {
;             const int k = (r & 1) ? (G - 1 - (int)blockIdx.x) : (int)blockIdx.x, i = r * G + k;
;             if (i < 4096) diff_tile(p, 63 - (i >> 6), i & 63, lam, smem);
.LBB0_816:
	s_add_i32 s17, s17, 1
	s_mul_i32 s6, s17, s58
	s_cmpk_gt_i32 s6, 0xfff
	s_cbranch_scc1 .LBB0_843
	.p2alignl 6, 3212836864

; __device__ __forceinline__ unsigned xb_ld(unsigned* p)              { return __hip_atomic_load(p, __ATOMIC_RELAXED, __HIP_MEMORY_SCOPE_AGENT); }
; __device__ __forceinline__ void xcd_barrier_complete(unsigned* bar, unsigned x, unsigned& nloc, unsigned& nx) {
;     const unsigned G = gridDim.x * gridDim.y * gridDim.z;
;     unsigned sum, cnt, mine, sp = 0u;
;     for (;;) {
;         sum = 0u; cnt = 0u; mine = 0u;
; #pragma unroll
;         for (unsigned j = 0; j < 16; ++j) { const unsigned c = xb_ld(&bar[XB_XCNT(j)]); sum += c; cnt += (c > 0u) ? 1u : 0u; mine = (j == x) ? c : mine; }
;         if (sum == G) break;
;         __builtin_amdgcn_s_sleep(1);
;         if ((++sp & 255u) == 0u) { if (xb_ld(&bar[XB_TMO])) break; if (sp > XB_SPIN_CAP) { atomicAdd(&bar[XB_TMO], 1u); break; } }
;     }
;     nloc = mine > 0u ? mine : 1u; nx = cnt > 0u ? cnt : 1u;
.LBB0_847:
	s_or_b64 exec, exec, s[10:11]
	s_and_b64 s[10:11], exec, s[6:7]
	s_or_b64 s[0:1], s[10:11], s[0:1]
	s_andn2_b64 s[2:3], s[2:3], exec
	s_and_b64 s[10:11], s[8:9], exec
	s_or_b64 s[2:3], s[2:3], s[10:11]
	s_andn2_b64 exec, exec, s[0:1]
	s_cbranch_execz .LBB0_855
	.p2alignl 6, 3212836864

; __device__ __forceinline__ void rmsnorm_phase(const float* x, const float* g, bf16_t* outb, float* outf) {
;     const int lane = threadIdx.x & 63;
;     const int gw = blockIdx.x * 4 + (threadIdx.x >> 6), nw = gridDim.x * 4;
;     f32x4 gv[4];
; #pragma unroll
;     for (int i = 0; i < 4; ++i) gv[i] = *(const f32x4*)(g + (lane + i * 64) * 4);
;     for (int row = gw; row < T; row += nw) {
;         const float* xr = x + (size_t)row * D;
;         f32x4 v[4];
;         float ss = 0.f;
; #pragma unroll
;         for (int i = 0; i < 4; ++i) { v[i] = __builtin_nontemporal_load((const f32x4*)(xr + (lane + i * 64) * 4)); ss += v[i][0] * v[i][0] + v[i][1] * v[i][1] + v[i][2] * v[i][2] + v[i][3] * v[i][3]; }
; #pragma unroll
;         for (int o = 32; o >= 1; o >>= 1) ss += __shfl_xor(ss, o);
.LBB0_943:
	s_or_b64 exec, exec, s[34:35]
	s_waitcnt lgkmcnt(0)
	s_barrier
	s_mov_b64 s[0:1], exec
	v_readlane_b32 s2, v245, 49
	v_readlane_b32 s3, v245, 50
	s_and_b64 s[2:3], s[0:1], s[2:3]
	s_mov_b64 exec, s[2:3]
	s_cbranch_execz .LBB0_946
	v_readlane_b32 s8, v245, 10
	v_readlane_b32 s9, v245, 11
	v_readlane_b32 s12, v245, 14
	v_readlane_b32 s13, v245, 15
	s_mov_b64 s[8:9], s[12:13]
	s_add_u32 s2, s8, 0x1000
	s_addc_u32 s3, s9, 0
	global_load_dwordx4 v[0:3], v168, s[2:3]
	global_load_dwordx4 v[4:7], v167, s[2:3]
	global_load_dwordx4 v[8:11], v146, s[2:3]
	global_load_dwordx4 v[12:15], v169, s[2:3]
	v_lshlrev_b64 v[16:17], 11, v[112:113]
	v_lshlrev_b64 v[18:19], 12, v[112:113]
	v_lshl_or_b32 v16, v115, 3, v16
	v_lshl_or_b32 v18, v115, 4, v18
	v_readlane_b32 s10, v245, 12
	v_readlane_b32 s11, v245, 13
	v_lshl_add_u64 v[16:17], s[56:57], 0, v[16:17]
	s_mov_b64 s[2:3], 0x3800000
	s_ashr_i32 s41, s40, 31
	v_lshl_add_u64 v[18:19], s[54:55], 0, v[18:19]
	s_mov_b64 s[6:7], 0xc00
	v_lshl_add_u64 v[16:17], v[16:17], 0, s[2:3]
	s_lshl_b64 s[2:3], s[40:41], 11
	v_lshl_add_u64 v[18:19], v[18:19], 0, s[6:7]
	s_lshl_b64 s[6:7], s[40:41], 12
	s_mov_b64 s[8:9], 0
	v_mov_b32_e32 v20, 0x358637bd
	s_mov_b32 s10, 0x800000
	s_movk_i32 s11, 0x7fff
	v_mov_b32_e32 v21, v112
	v_readlane_b32 s14, v245, 16
	v_readlane_b32 s15, v245, 17
	v_readlane_b32 s16, v245, 18
	v_readlane_b32 s17, v245, 19
	v_readlane_b32 s18, v245, 20
	v_readlane_b32 s19, v245, 21
	v_readlane_b32 s20, v245, 22
	v_readlane_b32 s21, v245, 23
	v_readlane_b32 s22, v245, 24
	v_readlane_b32 s23, v245, 25
	.p2alignl 6, 3212836864

; __device__ __forceinline__ unsigned xb_ld(unsigned* p)              { return __hip_atomic_load(p, __ATOMIC_RELAXED, __HIP_MEMORY_SCOPE_AGENT); }
; __device__ __forceinline__ void xcd_barrier_complete(unsigned* bar, unsigned x, unsigned& nloc, unsigned& nx) {
;     const unsigned G = gridDim.x * gridDim.y * gridDim.z;
;     unsigned sum, cnt, mine, sp = 0u;
;     for (;;) {
;         sum = 0u; cnt = 0u; mine = 0u;
; #pragma unroll
;         for (unsigned j = 0; j < 16; ++j) { const unsigned c = xb_ld(&bar[XB_XCNT(j)]); sum += c; cnt += (c > 0u) ? 1u : 0u; mine = (j == x) ? c : mine; }
;         if (sum == G) break;
;         __builtin_amdgcn_s_sleep(1);
;         if ((++sp & 255u) == 0u) { if (xb_ld(&bar[XB_TMO])) break; if (sp > XB_SPIN_CAP) { atomicAdd(&bar[XB_TMO], 1u); break; } }
;     }
;     nloc = mine > 0u ? mine : 1u; nx = cnt > 0u ? cnt : 1u;
.LBB0_1062:
	s_or_b64 exec, exec, s[8:9]
	s_and_b64 s[8:9], exec, s[4:5]
	s_or_b64 s[0:1], s[8:9], s[0:1]
	s_andn2_b64 s[2:3], s[2:3], exec
	s_and_b64 s[8:9], s[6:7], exec
	s_or_b64 s[2:3], s[2:3], s[8:9]
	s_andn2_b64 exec, exec, s[0:1]
	s_cbranch_execz .LBB0_1070
	.p2alignl 6, 3212836864

; __device__ __forceinline__ unsigned xb_ld(unsigned* p)              { return __hip_atomic_load(p, __ATOMIC_RELAXED, __HIP_MEMORY_SCOPE_AGENT); }
; #define XB_SPIN(cond, bar) do { unsigned _sp = 0; while (cond) { __builtin_amdgcn_s_sleep(1); \
;     if ((++_sp & 255u) == 0u) { if (xb_ld(&(bar)[XB_TMO])) break; if (_sp > XB_SPIN_CAP) { atomicAdd(&(bar)[XB_TMO], 1u); break; } } } } while (0)
; __device__ __forceinline__ void gsync(const XcdBarrier& b) {
;     ...
;             else XB_SPIN(xb_ld(&bar[XB_TOPGEN]) == tg, bar);
.LBB0_1076:
	s_or_b64 exec, exec, s[16:17]
	s_and_b64 s[12:13], exec, s[12:13]
	s_or_b64 s[6:7], s[12:13], s[6:7]
	s_andn2_b64 s[8:9], s[8:9], exec
	s_and_b64 s[12:13], s[10:11], exec
	s_or_b64 s[8:9], s[8:9], s[12:13]
	s_andn2_b64 exec, exec, s[6:7]
	s_cbranch_execz .LBB0_1083
	.p2alignl 6, 3212836864

; __device__ __forceinline__ unsigned xb_ld(unsigned* p)              { return __hip_atomic_load(p, __ATOMIC_RELAXED, __HIP_MEMORY_SCOPE_AGENT); }
; #define XB_SPIN(cond, bar) do { unsigned _sp = 0; while (cond) { __builtin_amdgcn_s_sleep(1); \
;     if ((++_sp & 255u) == 0u) { if (xb_ld(&(bar)[XB_TMO])) break; if (_sp > XB_SPIN_CAP) { atomicAdd(&(bar)[XB_TMO], 1u); break; } } } } while (0)
; __device__ __forceinline__ void gsync(const XcdBarrier& b) {
;     ...
;             XB_SPIN(xb_ld(&bar[XB_XGEN(bx)]) == gen, bar);
.LBB0_1090:
	s_or_b64 exec, exec, s[18:19]
	s_xor_b64 s[12:13], s[12:13], -1
	s_and_b64 s[14:15], exec, s[16:17]
	s_or_b64 s[8:9], s[14:15], s[8:9]
	s_andn2_b64 s[10:11], s[10:11], exec
	s_and_b64 s[12:13], s[12:13], exec
	s_or_b64 s[10:11], s[10:11], s[12:13]
	s_andn2_b64 exec, exec, s[8:9]
	s_cbranch_execz .LBB0_1097
	.p2alignl 6, 3212836864

; __device__ __forceinline__ void rmsnorm_phase(const float* x, const float* g, bf16_t* outb, float* outf) {
;     const int lane = threadIdx.x & 63;
;     const int gw = blockIdx.x * 4 + (threadIdx.x >> 6), nw = gridDim.x * 4;
;     f32x4 gv[4];
; #pragma unroll
;     for (int i = 0; i < 4; ++i) gv[i] = *(const f32x4*)(g + (lane + i * 64) * 4);
;     for (int row = gw; row < T; row += nw) {
;         const float* xr = x + (size_t)row * D;
;         f32x4 v[4];
;         float ss = 0.f;
; #pragma unroll
;         for (int i = 0; i < 4; ++i) { v[i] = __builtin_nontemporal_load((const f32x4*)(xr + (lane + i * 64) * 4)); ss += v[i][0] * v[i][0] + v[i][1] * v[i][1] + v[i][2] * v[i][2] + v[i][3] * v[i][3]; }
; #pragma unroll
;         for (int o = 32; o >= 1; o >>= 1) ss += __shfl_xor(ss, o);
.LBB0_1102:
	s_or_b64 exec, exec, s[30:31]
	v_readlane_b32 s2, v245, 49
	v_readlane_b32 s3, v245, 50
	s_waitcnt lgkmcnt(0)
	s_barrier
	s_and_saveexec_b64 s[0:1], s[2:3]
	s_cbranch_execz .LBB0_1105
	global_load_dwordx4 v[0:3], v146, s[52:53]
	global_load_dwordx4 v[4:7], v146, s[52:53] offset:1024
	global_load_dwordx4 v[8:11], v146, s[52:53] offset:2048
	global_load_dwordx4 v[12:15], v146, s[52:53] offset:3072
	v_lshlrev_b64 v[16:17], 12, v[112:113]
	v_lshl_or_b32 v16, v115, 4, v16
	v_lshl_add_u64 v[16:17], s[54:55], 0, v[16:17]
	s_mov_b64 s[0:1], 0xc00
	s_ashr_i32 s41, s40, 31
	v_lshl_add_u64 v[16:17], v[16:17], 0, s[0:1]
	s_lshl_b64 s[2:3], s[40:41], 12
	s_mov_b64 s[4:5], 0
	v_mov_b32_e32 v18, 0x358637bd
	s_mov_b32 s6, 0x800000
	s_movk_i32 s7, 0x7fff
	.p2alignl 6, 3212836864
